# e13: dm_gen + wo2_convert relocated from the P9 side path to 96 idle WGs beside P7's 12th GEMM round (strides rescaled 64->96 WGs), on top of e11+DMA nt
# baseline (speedup 1.0000x reference)
.LBB0_1153:
	s_cmp_gt_u32 s2, 159
	s_cbranch_scc0 .Le13_cont
	v_writelane_b32 v254, s4, 27
	v_writelane_b32 v254, s5, 28
	v_writelane_b32 v254, s16, 29
	v_writelane_b32 v254, s18, 30
	v_writelane_b32 v254, s19, 31
	v_writelane_b32 v254, s21, 32
	v_writelane_b32 v254, s23, 33
	v_writelane_b32 v254, s28, 34
	s_movk_i32 s99, 0x5a5a
	s_add_i32 s21, s2, 0xffffff60
	s_branch .Le13_dm_entry

.LBB0_1334:
	s_cmpk_eq_u32 s99, 0x5a5a
	s_cbranch_scc0 .LBB0_1408
.Le13_dm_entry:
	s_bitcmp1_b32 s90, 2
	s_cbranch_scc1 .LBB0_1373
	s_cmpk_gt_i32 s2, 0x20bf
	s_cbranch_scc1 .LBB0_1373
	s_mul_i32 s4, s21, 0x2100
	s_mul_hi_i32 s5, s21, 0x2100
	s_add_u32 s4, s92, s4
	s_waitcnt vmcnt(0)
	v_lshlrev_b32_e32 v2, 4, v0
	v_mov_b32_e32 v3, 0
	s_addc_u32 s5, s93, s5
	s_movk_i32 s0, 0x210
	v_lshl_add_u64 v[2:3], s[4:5], 0, v[2:3]
	s_mov_b64 s[4:5], 0x11200000
	v_lshlrev_b32_e32 v1, 3, v0
	v_cmp_gt_u32_e64 s[0:1], s0, v0
	v_lshl_add_u64 v[2:3], v[2:3], 0, s[4:5]
	v_or_b32_e32 v6, 7, v1
	v_or_b32_e32 v7, 1, v1
	s_add_i32 s22, s21, 0x1000
	v_or_b32_e32 v8, 2, v1
	v_or_b32_e32 v9, 3, v1
	v_or_b32_e32 v10, 4, v1
	v_or_b32_e32 v11, 5, v1
	v_or_b32_e32 v12, 6, v1
	s_movk_i32 s23, 0xfff
	s_movk_i32 s24, 0x201
	s_movk_i32 s25, 0x200
	s_movk_i32 s26, 0x1001
	s_mov_b64 s[6:7], 0x2000
	s_mov_b64 s[8:9], 0xc6000
	s_branch .LBB0_1338
.LBB0_1337:
	s_or_b64 exec, exec, s[10:11]
	s_add_i32 s4, s21, 96
	s_add_i32 s22, s22, 96
	v_lshl_add_u64 v[2:3], v[2:3], 0, s[8:9]
	s_cmpk_gt_i32 s21, 0x1f9f
	s_mov_b32 s21, s4
	s_cbranch_scc1 .LBB0_1373

.LBB0_1373:
	s_lshl_b32 s0, s2, 3
	s_add_i32 s0, s0, s33
	s_add_i32 s8, s0, 0xfffffb00
	s_cmpk_gt_i32 s8, 0x1fff
	s_waitcnt vmcnt(0)
	s_barrier
	s_cbranch_scc1 .LBB0_1408
	s_mul_i32 s0, s33, 0x2100
	s_add_i32 s4, s0, 0
	v_lshrrev_b32_e32 v8, 5, v162
	s_movk_i32 s0, 0x84
	v_mov_b32_e32 v2, 0x210
	v_mad_u32_u24 v43, v8, s0, v2
	v_mov_b32_e32 v2, 0x420
	v_mad_u32_u24 v44, v8, s0, v2
	v_mov_b32_e32 v2, 0x630
	v_mad_u32_u24 v45, v8, s0, v2
	v_mov_b32_e32 v2, 0x840
	v_mad_u32_u24 v46, v8, s0, v2
	v_lshlrev_b32_e32 v2, 3, v0
	v_and_b32_e32 v2, 56, v2
	v_and_b32_e32 v1, 31, v0
	v_lshrrev_b32_e32 v40, 3, v162
	v_mul_u32_u24_e32 v41, 0x84, v2
	v_lshlrev_b32_e32 v2, 1, v2
	v_mov_b32_e32 v3, 0
	v_lshl_add_u32 v6, v1, 2, s4
	v_mul_u32_u24_e32 v7, 0x84, v8
	v_lshl_add_u64 v[4:5], s[92:93], 0, v[2:3]
	s_mov_b64 s[0:1], 0xf200000
	v_lshlrev_b32_e32 v2, 2, v40
	v_or_b32_e32 v9, 2, v8
	v_or_b32_e32 v10, 4, v8
	v_or_b32_e32 v11, 6, v8
	v_or_b32_e32 v12, 8, v8
	v_or_b32_e32 v13, 10, v8
	v_or_b32_e32 v14, 12, v8
	v_or_b32_e32 v15, 14, v8
	v_or_b32_e32 v16, 16, v8
	v_or_b32_e32 v17, 18, v8
	v_or_b32_e32 v18, 20, v8
	v_or_b32_e32 v19, 22, v8
	v_or_b32_e32 v20, 24, v8
	v_or_b32_e32 v21, 26, v8
	v_or_b32_e32 v22, 28, v8
	v_or_b32_e32 v23, 30, v8
	v_or_b32_e32 v24, 32, v8
	v_or_b32_e32 v25, 34, v8
	v_or_b32_e32 v26, 36, v8
	v_or_b32_e32 v27, 38, v8
	v_or_b32_e32 v28, 40, v8
	v_or_b32_e32 v29, 42, v8
	v_or_b32_e32 v30, 44, v8
	v_or_b32_e32 v31, 46, v8
	v_or_b32_e32 v32, 48, v8
	v_or_b32_e32 v33, 50, v8
	v_or_b32_e32 v34, 52, v8
	v_or_b32_e32 v35, 54, v8
	v_or_b32_e32 v36, 56, v8
	v_or_b32_e32 v37, 58, v8
	v_or_b32_e32 v38, 60, v8
	v_or_b32_e32 v39, 62, v8
	v_lshl_add_u64 v[4:5], v[4:5], 0, s[0:1]
	v_add3_u32 v41, s4, v41, v2
	s_lshl_b32 s9, s8, 5
	v_add_u32_e32 v42, v6, v7
	v_add_u32_e32 v43, v6, v43
	v_add_u32_e32 v44, v6, v44
	v_add_u32_e32 v45, v6, v45
	v_add_u32_e32 v46, v6, v46
	s_branch .LBB0_1376
.LBB0_1375:
	s_waitcnt vmcnt(0)
	ds_write2_b32 v2, v47, v48 offset0:172 offset1:238
	s_waitcnt lgkmcnt(0)
	s_sub_i32 s4, 0, s1
	ds_read2_b32 v[6:7], v41 offset1:33
	s_add_i32 s4, s4, s9
	s_waitcnt lgkmcnt(0)
	v_cvt_pk_bf16_f32 v48, v6, v7
	ds_read2_b32 v[6:7], v41 offset0:66 offset1:99
	v_add_u32_e32 v54, s4, v40
	s_waitcnt lgkmcnt(0)
	v_cvt_pk_bf16_f32 v49, v6, v7
	ds_read2_b32 v[6:7], v41 offset0:132 offset1:165
	s_ashr_i32 s1, s0, 31
	v_ashrrev_i32_e32 v55, 31, v54
	s_waitcnt lgkmcnt(0)
	v_cvt_pk_bf16_f32 v50, v6, v7
	ds_read2_b32 v[6:7], v41 offset0:198 offset1:231
	v_lshl_add_u64 v[52:53], s[0:1], 1, v[4:5]
	v_lshlrev_b64 v[56:57], 13, v[54:55]
	s_waitcnt lgkmcnt(0)
	v_cvt_pk_bf16_f32 v51, v6, v7
	ds_read2_b32 v[6:7], v41 offset0:8 offset1:41
	v_lshl_add_u64 v[56:57], v[52:53], 0, v[56:57]
	global_store_dwordx4 v[56:57], v[48:51], off
	v_add_u32_e32 v56, 8, v54
	v_ashrrev_i32_e32 v57, 31, v56
	s_waitcnt lgkmcnt(0)
	v_cvt_pk_bf16_f32 v48, v6, v7
	ds_read2_b32 v[6:7], v41 offset0:74 offset1:107
	s_waitcnt lgkmcnt(0)
	v_cvt_pk_bf16_f32 v49, v6, v7
	ds_read2_b32 v[6:7], v41 offset0:140 offset1:173
	s_waitcnt lgkmcnt(0)
	v_cvt_pk_bf16_f32 v50, v6, v7
	ds_read2_b32 v[6:7], v41 offset0:206 offset1:239
	v_lshlrev_b64 v[56:57], 13, v[56:57]
	s_waitcnt lgkmcnt(0)
	v_cvt_pk_bf16_f32 v51, v6, v7
	ds_read2_b32 v[6:7], v41 offset0:16 offset1:49
	v_lshl_add_u64 v[56:57], v[52:53], 0, v[56:57]
	global_store_dwordx4 v[56:57], v[48:51], off
	v_add_u32_e32 v56, 16, v54
	v_ashrrev_i32_e32 v57, 31, v56
	s_waitcnt lgkmcnt(0)
	v_cvt_pk_bf16_f32 v48, v6, v7
	ds_read2_b32 v[6:7], v41 offset0:82 offset1:115
	s_waitcnt lgkmcnt(0)
	v_cvt_pk_bf16_f32 v49, v6, v7
	ds_read2_b32 v[6:7], v41 offset0:148 offset1:181
	s_waitcnt lgkmcnt(0)
	v_cvt_pk_bf16_f32 v50, v6, v7
	ds_read2_b32 v[6:7], v41 offset0:214 offset1:247
	v_lshlrev_b64 v[56:57], 13, v[56:57]
	v_add_u32_e32 v54, 24, v54
	s_waitcnt lgkmcnt(0)
	v_cvt_pk_bf16_f32 v51, v6, v7
	ds_read2_b32 v[6:7], v41 offset0:24 offset1:57
	v_lshl_add_u64 v[56:57], v[52:53], 0, v[56:57]
	v_ashrrev_i32_e32 v55, 31, v54
	global_store_dwordx4 v[56:57], v[48:51], off
	v_lshlrev_b64 v[54:55], 13, v[54:55]
	v_lshl_add_u64 v[52:53], v[52:53], 0, v[54:55]
	s_waitcnt lgkmcnt(0)
	v_cvt_pk_bf16_f32 v48, v6, v7
	ds_read2_b32 v[6:7], v41 offset0:90 offset1:123
	s_waitcnt lgkmcnt(0)
	v_cvt_pk_bf16_f32 v49, v6, v7
	ds_read2_b32 v[6:7], v41 offset0:156 offset1:189
	s_waitcnt lgkmcnt(0)
	v_cvt_pk_bf16_f32 v50, v6, v7
	ds_read2_b32 v[6:7], v41 offset0:222 offset1:255
	s_waitcnt lgkmcnt(0)
	v_cvt_pk_bf16_f32 v51, v6, v7
	global_store_dwordx4 v[52:53], v[48:51], off
	s_waitcnt lgkmcnt(0)
	s_add_i32 s0, s8, 0x300
	v_add_u32_e32 v40, 0x6000, v40
	v_add_u32_e32 v1, 0x6000, v1
	s_cmpk_lt_i32 s8, 0x1d00
	s_mov_b32 s8, s0
	s_cbranch_scc0 .LBB0_1408

.LBB0_1408:
	s_cmpk_eq_u32 s99, 0x5a5a
	s_cbranch_scc0 .Le13_norm
	s_mov_b32 s99, 0
	s_waitcnt vmcnt(0) lgkmcnt(0)
	v_readlane_b32 s4, v254, 27
	v_readlane_b32 s5, v254, 28
	v_readlane_b32 s16, v254, 29
	v_readlane_b32 s18, v254, 30
	v_readlane_b32 s19, v254, 31
	v_readlane_b32 s21, v254, 32
	v_readlane_b32 s23, v254, 33
	v_readlane_b32 s28, v254, 34
	s_nop 4
	s_branch .Le13_cont
